# speedup vs baseline: 1.0073x; 1.0073x over previous
; DI u32x4 pack8(f32x4 a, f32x4 b) { u32x4 w; w.x = cvt_pk_bf16(a[0], a[1]); w.y = cvt_pk_bf16(a[2], a[3]); w.z = cvt_pk_bf16(b[0], b[1]); w.w = cvt_pk_bf16(b[2], b[3]); return w; }
; DI void conv_copy(const float* __restrict__ src, bf16_t* __restrict__ dst, size_t n) {
;     for (size_t i = ((size_t)blockIdx.x * 512 + threadIdx.x) * 8; i < n; i += (size_t)gridDim.x * 512 * 8)
;         *(u32x4*)(dst + i) = pack8(*(const f32x4*)(src + i), *(const f32x4*)(src + i + 4));
; }
.LBB0_842:
	s_cmpk_lg_u32 s26, 0x100
	s_cbranch_scc1 .Lcc_generic
	s_and_saveexec_b64 s[50:51], vcc
	s_cbranch_execz .Lcc_l1
	global_load_dwordx4 v[152:155], v[2:3], off offset:-16
	global_load_dwordx4 v[156:159], v[2:3], off
.Lcc_l1:
	s_or_b64 exec, exec, s[50:51]
	v_lshl_add_u64 v[14:15], v[6:7], 0, s[12:13]
	global_load_dwordx4 v[160:163], v[6:7], off offset:-16
	global_load_dwordx4 v[224:227], v[6:7], off
	global_load_dwordx4 v[228:231], v[14:15], off offset:-16
	global_load_dwordx4 v[232:235], v[14:15], off
	s_and_saveexec_b64 s[50:51], s[8:9]
	s_cbranch_execz .Lcc_l3
	global_load_dwordx4 v[236:239], v[10:11], off offset:-16
	global_load_dwordx4 v[240:243], v[10:11], off
.Lcc_l3:
	s_or_b64 exec, exec, s[50:51]
	s_waitcnt vmcnt(0)
	v_cvt_pk_bf16_f32 v20, v160, v161
	v_cvt_pk_bf16_f32 v21, v162, v163
	v_cvt_pk_bf16_f32 v22, v224, v225
	v_cvt_pk_bf16_f32 v23, v226, v227
	global_store_dwordx4 v[8:9], v[20:23], off
	v_lshl_add_u64 v[16:17], v[8:9], 0, s[30:31]
	v_cvt_pk_bf16_f32 v24, v228, v229
	v_cvt_pk_bf16_f32 v25, v230, v231
	v_cvt_pk_bf16_f32 v26, v232, v233
	v_cvt_pk_bf16_f32 v27, v234, v235
	global_store_dwordx4 v[16:17], v[24:27], off
	s_and_saveexec_b64 s[50:51], vcc
	s_cbranch_execz .Lcc_s1
	v_cvt_pk_bf16_f32 v152, v152, v153
	v_cvt_pk_bf16_f32 v153, v154, v155
	v_cvt_pk_bf16_f32 v154, v156, v157
	v_cvt_pk_bf16_f32 v155, v158, v159
	s_nop 0
	global_store_dwordx4 v[4:5], v[152:155], off
.Lcc_s1:
	s_or_b64 exec, exec, s[50:51]
	s_and_saveexec_b64 s[50:51], s[8:9]
	s_cbranch_execz .LBB0_841
	v_cvt_pk_bf16_f32 v236, v236, v237
	v_cvt_pk_bf16_f32 v237, v238, v239
	v_cvt_pk_bf16_f32 v238, v240, v241
	v_cvt_pk_bf16_f32 v239, v242, v243
	s_nop 0
	global_store_dwordx4 v[12:13], v[236:239], off
	s_branch .LBB0_841
